# attention: hoist all V-fragment LDS reads before exp section + double-buffered K/V LDS tiles with one barrier per tile (on top of far-tile fast path, relu2 epilogue, scan sa)
# speedup vs baseline: 1.0020x; 1.0020x over previous
; #define LAS __attribute__((address_space(3)))
;     __device__ __forceinline__ const float* in(int i) const { return (const float*)(const __attribute__((address_space(1))) float*)ld(i); }
;     __device__ __forceinline__ unsigned char* wsp() const { return (unsigned char*)(__attribute__((address_space(1))) unsigned char*)ld(33); }
; __device__ __forceinline__ void phase_attn(const DArgs& a, LAS unsigned char* lds) {
;     const int tid = threadIdx.x, wave = tid >> 6, lane = tid & 63, fr = lane & 15, g = lane >> 4;
;     const bf16_t* qk = (const bf16_t*)(a.wsp() + W_QK); const bf16_t* vT = (const bf16_t*)(a.wsp() + W_VT);
;     const bf16_t* Ks = (const bf16_t*)(a.wsp() + W_KS); const bf16_t* VsT = (const bf16_t*)(a.wsp() + W_VST);
;     const float* relb = a.in(I_RELB);
;     bf16_t* oatt = (bf16_t*)(a.wsp() + W_MIX);
;     LAS float* biasT = (LAS float*)(lds + A_B);
;     const float scale = 0.08838834764831845f;
;     constexpr int NITEMS = 2048 + 128;
;     struct Item { int h, qrow, qpos, tile_lo, tile_hi, qc, nkeys, ldk, ldv, kpos_base; const bf16_t* Kb; const bf16_t* Vb; bool wact, prompt; };
;     auto setup = [&](int it) -> Item { Item I; I.prompt = it < 2048; I.qc = 0;
;         if (I.prompt) { const int pi = it >> 4; I.h = it & 15; I.qc = 2 * pi + (wave >> 2); I.qrow = I.qc * 64 + (wave & 3) * 16 + fr; I.qpos = I.qrow;
;             I.tile_lo = 2 * pi - 8 < 0 ? 0 : 2 * pi - 8; I.tile_hi = 2 * pi + 1; I.nkeys = 1 << 30; I.ldk = 4096; I.ldv = TA; I.kpos_base = 0;
;             I.Kb = qk + 2048 + I.h * 128; I.Vb = vT + (size_t)(I.h * 128) * TA; I.wact = true; }
;         else { const int s_ = it - 2048, b = s_ >> 4; I.h = s_ & 15; const int w2 = wave & 1; I.qrow = TP + b * 32 + w2 * 16 + fr; I.qpos = 2048 + w2 * 16 + fr;
;             I.tile_lo = 0; I.tile_hi = 8; I.nkeys = 544; I.ldk = D; I.ldv = 576; I.kpos_base = 1536;
;             I.Kb = Ks + (size_t)b * 576 * D + I.h * 128; I.Vb = VsT + ((size_t)b * D + I.h * 128) * 576; I.wact = wave < 2; }
;         return I; };
;     u32x4 kreg[2], vreg[2];
;     const int kr = tid >> 4, kc = tid & 15, vr = tid >> 3, vc = tid & 7;
;     ...
;     if ((int)blockIdx.x >= NITEMS) return;
;     Item cur = setup(blockIdx.x);
;     bf16x8 qf[4], qfn[4];
;     float biasn = tid < 257 ? relb[cur.h * 257 + tid] : 0.f;
;     ATT_LOADQ(qf, cur);
;     ATT_LOAD(cur, cur.tile_lo);
.LBB0_1355:
	s_cmp_lt_i32 s78, 17
	s_cselect_b64 s[6:7], -1, 0
	s_and_b64 s[0:1], s[6:7], s[0:1]
	s_andn2_b64 vcc, exec, s[0:1]
	s_cbranch_vccnz .LBB0_1397
	s_mov_b32 s101, 0xa000
	s_add_i32 s0, 0, 0x200e0
	s_add_i32 s1, 0, 0x20108
	v_mov_b32_e32 v0, s1
	v_mov_b32_e32 v2, s0
	ds_read_b64 v[0:1], v0
	ds_read_b64 v[2:3], v2
	s_cmpk_gt_i32 s2, 0x87f
	s_waitcnt lgkmcnt(1)
	v_readfirstlane_b32 s24, v1
	v_readfirstlane_b32 s25, v0
	s_waitcnt lgkmcnt(0)
	v_readfirstlane_b32 s9, v3
	v_readfirstlane_b32 s8, v2
	s_cbranch_scc1 .LBB0_1397
	s_cmpk_lt_i32 s2, 0x800
	s_cselect_b64 s[14:15], -1, 0
	s_and_b32 s54, s2, 15
	s_lshl_b32 s20, s54, 7
	s_add_u32 s48, s25, 0x1ce58000
	s_addc_u32 s49, s24, 0
	s_add_u32 s50, s25, 0x20f58000
	s_addc_u32 s51, s24, 0
	s_add_u32 s52, s25, 0x22158000
	v_lshrrev_b32_e32 v0, 2, v166
	v_and_b32_e32 v33, 15, v166
	s_addc_u32 s53, s24, 0
	v_and_b32_e32 v1, 16, v0
	s_movk_i32 s0, 0x80
	s_movk_i32 s59, 0x800
	s_cmpk_gt_i32 s2, 0x7ff
	v_or_b32_e32 v34, v33, v1
	v_cmp_gt_u32_e64 s[10:11], s0, v166
	s_mov_b32 s61, 8
	s_cbranch_scc0 .LBB0_1359
	s_add_i32 s0, s2, 0xfffff800
	s_lshr_b32 s0, s0, 4
	s_lshl_b32 s1, s0, 5
	s_addk_i32 s1, 0x4000
	v_or3_b32 v98, s1, v1, v33
	s_mov_b32 s1, 0
	s_mul_hi_u32 s4, s0, 0x240000
	s_mul_i32 s5, s0, 0x240000
	s_lshl_b64 s[0:1], s[0:1], 11
	s_or_b32 s0, s0, s20
	s_mulk_i32 s1, 0x480
	s_mul_hi_u32 s16, s0, 0x480
	s_add_i32 s16, s16, s1
	s_add_u32 s18, s50, s5
	s_mulk_i32 s0, 0x480
	s_addc_u32 s19, s51, s4
	s_add_u32 s0, s52, s0
	s_addc_u32 s1, s53, s16
	s_mov_b64 s[4:5], 0
	s_branch .LBB0_1360

; #define LAS __attribute__((address_space(3)))
; __device__ __forceinline__ unsigned pk2(float lo, float hi) { unsigned r; asm("v_cvt_pk_bf16_f32 %0, %1, %2" : "=v"(r) : "v"(lo), "v"(hi)); return r; }
; __device__ __forceinline__ void phase_attn(const DArgs& a, LAS unsigned char* lds) {
;     ...
;                 tmax = fmaxf(tmax, __shfl_xor(tmax, 16)); tmax = fmaxf(tmax, __shfl_xor(tmax, 32));
;                 const float mnew = fmaxf(mrun, tmax), alpha = __expf(mrun - mnew); mrun = mnew;
;                 float psum = 0.f;
; #pragma unroll
;                 for (int kt = 0; kt < 4; ++kt)
; #pragma unroll
;                     for (int r = 0; r < 4; ++r) { const float p_ = __expf(sacc[kt][r] - mnew); sacc[kt][r] = p_; psum += p_; }
;                 lrun = lrun * alpha + psum;
; #pragma unroll
;                 for (int n = 0; n < 8; ++n) oacc[n] = oacc[n] * alpha;
; #pragma unroll
;                 for (int j = 0; j < 2; ++j) {
;                     u32x4 pw; pw.x = pk2(sacc[2 * j][0], sacc[2 * j][1]); pw.y = pk2(sacc[2 * j][2], sacc[2 * j][3]); pw.z = pk2(sacc[2 * j + 1][0], sacc[2 * j + 1][1]); pw.w = pk2(sacc[2 * j + 1][2], sacc[2 * j + 1][3]);
;                     const bf16x8 pf = __builtin_bit_cast(bf16x8, pw);
; #pragma unroll
;                     for (int n = 0; n < 8; ++n) {
;                         const u32x2 v0 = *(const LAS u32x2*)(lds + A_V + (16 * n + fr) * VT_LD + (32 * j + 4 * g) * 2);
;                         const u32x2 v1 = *(const LAS u32x2*)(lds + A_V + (16 * n + fr) * VT_LD + (32 * j + 16 + 4 * g) * 2);
;                         const bf16x8 vf = __builtin_bit_cast(bf16x8, (u32x4){v0.x, v0.y, v1.x, v1.y});
;                         oacc[n] = __builtin_amdgcn_mfma_f32_16x16x32_bf16(vf, pf, oacc[n], 0, 0, 0);
;                     }
.Lattn_join:
	v_and_b32_e32 v150, 64, v142
	v_xor_b32_e32 v147, 16, v142
	v_add_u32_e32 v150, 64, v150
	v_cmp_lt_i32_e32 vcc, v147, v150
	v_add_u32_e32 v171, 0x5800, v137
	v_add_u32_e32 v172, 0x6800, v137
	v_cndmask_b32_e32 v147, v142, v147, vcc
	v_lshlrev_b32_e32 v147, 2, v147
	ds_bpermute_b32 v147, v147, v80
	v_add_u32_e32 v170, 0x5000, v137
	v_add_u32_e32 v174, 0x7800, v137
	v_add_u32_e32 v175, 0x8000, v137
	v_add_u32_e32 v173, 0x7000, v137
	s_waitcnt lgkmcnt(0)
	v_max_f32_e32 v147, v147, v147
	v_max_f32_e32 v80, v80, v147
	v_xor_b32_e32 v147, 32, v142
	v_cmp_lt_i32_e32 vcc, v147, v150
	s_nop 1
	v_cndmask_b32_e32 v147, v142, v147, vcc
	v_lshlrev_b32_e32 v147, 2, v147
	ds_bpermute_b32 v147, v147, v80
	s_waitcnt lgkmcnt(0)
	ds_read2_b64 v[182:185], v165 offset0:128 offset1:132
	ds_read2_b64 v[186:189], v169 offset0:160 offset1:164
	ds_read2_b64 v[190:193], v171 offset0:224 offset1:228
	ds_read2_b64 v[194:197], v170 offset0:192 offset1:196
	ds_read2_b64 v[198:201], v172 offset1:4
	ds_read2_b64 v[202:205], v174 offset0:64 offset1:68
	ds_read2_b64 v[206:209], v175 offset0:96 offset1:100
	ds_read2_b64 v[210:213], v173 offset0:32 offset1:36
	ds_read2_b64 v[214:217], v165 offset0:136 offset1:140
	ds_read2_b64 v[218:221], v169 offset0:168 offset1:172
	ds_read2_b64 v[222:225], v170 offset0:200 offset1:204
	ds_read2_b64 v[226:229], v171 offset0:232 offset1:236
	ds_read2_b64 v[230:233], v172 offset0:8 offset1:12
	ds_read2_b64 v[234:237], v173 offset0:40 offset1:44
	ds_read2_b64 v[238:241], v174 offset0:72 offset1:76
	ds_read2_b64 v[242:245], v175 offset0:104 offset1:108
	v_max3_f32 v147, v148, v80, v147
	v_sub_f32_e32 v82, v82, v147
	v_mul_f32_e32 v82, 0x3fb8aa3b, v82
	v_exp_f32_e32 v153, v82
	v_sub_f32_e32 v82, v83, v147
	v_mul_f32_e32 v82, 0x3fb8aa3b, v82
	v_exp_f32_e32 v154, v82
	v_sub_f32_e32 v82, v84, v147
	v_mul_f32_e32 v82, 0x3fb8aa3b, v82
	v_exp_f32_e32 v155, v82
	v_sub_f32_e32 v82, v85, v147
	v_mul_f32_e32 v82, 0x3fb8aa3b, v82
	v_exp_f32_e32 v156, v82
	v_sub_f32_e32 v82, v86, v147
	v_mul_f32_e32 v82, 0x3fb8aa3b, v82
	v_exp_f32_e32 v157, v82
	v_sub_f32_e32 v82, v87, v147
	v_mul_f32_e32 v82, 0x3fb8aa3b, v82
	v_exp_f32_e32 v158, v82
	v_sub_f32_e32 v82, v92, v147
	v_mul_f32_e32 v82, 0x3fb8aa3b, v82
	v_exp_f32_e32 v159, v82
	v_sub_f32_e32 v82, v93, v147
	v_mul_f32_e32 v82, 0x3fb8aa3b, v82
	v_exp_f32_e32 v160, v82
	v_sub_f32_e32 v82, v94, v147
	v_mul_f32_e32 v82, 0x3fb8aa3b, v82
	v_exp_f32_e32 v94, v82
	v_sub_f32_e32 v82, v95, v147
	v_mul_f32_e32 v82, 0x3fb8aa3b, v82
	v_exp_f32_e32 v95, v82
	v_sub_f32_e32 v82, v88, v147
	v_mul_f32_e32 v82, 0x3fb8aa3b, v82
	v_exp_f32_e32 v161, v82
	v_sub_f32_e32 v82, v89, v147
	v_mul_f32_e32 v82, 0x3fb8aa3b, v82
	v_exp_f32_e32 v162, v82
	v_sub_f32_e32 v82, v90, v147
	v_mul_f32_e32 v82, 0x3fb8aa3b, v82
	v_exp_f32_e32 v163, v82
	v_sub_f32_e32 v82, v91, v147
	v_mul_f32_e32 v164, 0x3fb8aa3b, v82
	s_nop 0
	s_nop 0
	v_sub_f32_e32 v80, v148, v147
	v_sub_f32_e32 v81, v81, v147
	v_mul_f32_e32 v80, 0x3fb8aa3b, v80
	v_mul_f32_e32 v81, 0x3fb8aa3b, v81
	v_exp_f32_e32 v81, v81
	v_exp_f32_e32 v80, v80
	v_sub_f32_e32 v148, v149, v147
	v_mul_f32_e32 v148, 0x3fb8aa3b, v148
	v_exp_f32_e32 v152, v148
	v_pk_mul_f32 v[62:63], v[62:63], v[80:81] op_sel_hi:[1,0]
	v_pk_mul_f32 v[60:61], v[60:61], v[80:81] op_sel_hi:[1,0]
	v_pk_mul_f32 v[58:59], v[58:59], v[80:81] op_sel_hi:[1,0]
	v_pk_mul_f32 v[56:57], v[56:57], v[80:81] op_sel_hi:[1,0]
	v_cvt_pk_bf16_f32 v86, v152, v81
	v_cvt_pk_bf16_f32 v87, v153, v154
	v_cvt_pk_bf16_f32 v88, v155, v156
	v_cvt_pk_bf16_f32 v89, v157, v158
	v_pk_mul_f32 v[50:51], v[50:51], v[80:81] op_sel_hi:[1,0]
	s_waitcnt lgkmcnt(15)
	v_mfma_f32_16x16x32_bf16 v[60:63], v[182:185], v[86:89], v[60:63]
	s_nop 0
	v_pk_mul_f32 v[48:49], v[48:49], v[80:81] op_sel_hi:[1,0]
	s_nop 0
	s_waitcnt lgkmcnt(14)
	v_mfma_f32_16x16x32_bf16 v[56:59], v[186:189], v[86:89], v[56:59]
	s_nop 0
	v_pk_mul_f32 v[46:47], v[46:47], v[80:81] op_sel_hi:[1,0]
	v_pk_mul_f32 v[44:45], v[44:45], v[80:81] op_sel_hi:[1,0]
	s_waitcnt lgkmcnt(13)
	v_mfma_f32_16x16x32_bf16 v[48:51], v[190:193], v[86:89], v[48:51]
	s_nop 0
	v_pk_mul_f32 v[54:55], v[54:55], v[80:81] op_sel_hi:[1,0]
	v_pk_mul_f32 v[52:53], v[52:53], v[80:81] op_sel_hi:[1,0]
	s_waitcnt lgkmcnt(11)
	v_mfma_f32_16x16x32_bf16 v[44:47], v[198:201], v[86:89], v[44:47]
	s_nop 0
	v_pk_mul_f32 v[38:39], v[38:39], v[80:81] op_sel_hi:[1,0]
	v_pk_mul_f32 v[36:37], v[36:37], v[80:81] op_sel_hi:[1,0]
	v_mfma_f32_16x16x32_bf16 v[52:55], v[194:197], v[86:89], v[52:55]
	s_nop 0
	v_pk_mul_f32 v[34:35], v[34:35], v[80:81] op_sel_hi:[1,0]
	v_pk_mul_f32 v[32:33], v[32:33], v[80:81] op_sel_hi:[1,0]
	s_waitcnt lgkmcnt(10)
	v_mfma_f32_16x16x32_bf16 v[36:39], v[202:205], v[86:89], v[36:39]
	s_nop 0
	v_pk_mul_f32 v[42:43], v[42:43], v[80:81] op_sel_hi:[1,0]
	v_pk_mul_f32 v[40:41], v[40:41], v[80:81] op_sel_hi:[1,0]
	s_waitcnt lgkmcnt(9)
	v_mfma_f32_16x16x32_bf16 v[32:35], v[206:209], v[86:89], v[32:35]
	s_nop 0
	v_exp_f32_e32 v164, v164
	s_waitcnt lgkmcnt(8)
	v_mfma_f32_16x16x32_bf16 v[40:43], v[210:213], v[86:89], v[40:43]
	v_cvt_pk_bf16_f32 v86, v159, v160
	v_cvt_pk_bf16_f32 v87, v94, v95
	v_cvt_pk_bf16_f32 v88, v161, v162
	v_cvt_pk_bf16_f32 v89, v163, v164
	s_nop 0
	s_waitcnt lgkmcnt(7)
	v_mfma_f32_16x16x32_bf16 v[60:63], v[214:217], v[86:89], v[60:63]
	v_add_f32_e32 v82, 0, v152
	v_add_f32_e32 v81, v81, v82
	s_nop 0
	s_waitcnt lgkmcnt(6)
	v_mfma_f32_16x16x32_bf16 v[56:59], v[218:221], v[86:89], v[56:59]
	s_nop 0
	v_add_f32_e32 v81, v153, v81
	v_add_f32_e32 v81, v154, v81
	v_add_f32_e32 v81, v155, v81
	s_waitcnt lgkmcnt(5)
	v_mfma_f32_16x16x32_bf16 v[52:55], v[222:225], v[86:89], v[52:55]
	v_add_f32_e32 v81, v156, v81
	s_nop 0
	v_add_f32_e32 v81, v157, v81
	s_waitcnt lgkmcnt(4)
	v_mfma_f32_16x16x32_bf16 v[48:51], v[226:229], v[86:89], v[48:51]
	s_nop 0
	v_add_f32_e32 v81, v158, v81
	v_add_f32_e32 v81, v159, v81
	s_waitcnt lgkmcnt(3)
	v_mfma_f32_16x16x32_bf16 v[44:47], v[230:233], v[86:89], v[44:47]
	s_nop 0
	v_add_f32_e32 v81, v160, v81
	v_add_f32_e32 v81, v94, v81
	v_add_f32_e32 v81, v95, v81
	v_add_f32_e32 v81, v161, v81
	v_add_f32_e32 v81, v162, v81
	s_waitcnt lgkmcnt(2)
	v_mfma_f32_16x16x32_bf16 v[40:43], v[234:237], v[86:89], v[40:43]
	v_add_f32_e32 v81, v163, v81
	v_add_f32_e32 v81, v164, v81
	v_fmac_f32_e32 v81, v99, v80
	s_waitcnt lgkmcnt(1)
	v_mfma_f32_16x16x32_bf16 v[36:39], v[238:241], v[86:89], v[36:39]
	v_mov_b32_e32 v99, v81
	v_mov_b32_e32 v148, v147
	s_waitcnt lgkmcnt(0)
	v_mfma_f32_16x16x32_bf16 v[32:35], v[242:245], v[86:89], v[32:35]

; #define ATT_STORE() do { _Pragma("unroll") for (int p_ = 0; p_ < 2; ++p_) { \
;         *(LAS u32x4*)(lds + A_K + (kr + 32 * p_) * KT_LD + kc * 16) = kreg[p_]; \
;         *(LAS u32x4*)(lds + A_V + (vr + 64 * p_) * VT_LD + vc * 16) = vreg[p_]; } } while (0)
; __device__ __forceinline__ void phase_attn(const DArgs& a, LAS unsigned char* lds) {
;     ...
;             if (tile < cur.tile_hi) { __syncthreads(); ATT_STORE(); __syncthreads(); }
.LBB0_1391:
	v_add_u32_e32 v138, s101, v138
	v_add_u32_e32 v139, s101, v139
	s_waitcnt vmcnt(3)
	ds_write_b128 v138, v[8:11]
	s_waitcnt vmcnt(2)
	ds_write_b128 v139, v[4:7] offset:17408
	s_waitcnt vmcnt(1)
	ds_write_b128 v138, v[12:15] offset:8704
	s_waitcnt vmcnt(0)
	ds_write_b128 v139, v[0:3] offset:26624
	v_add_u32_e32 v136, s101, v136
	v_add_u32_e32 v137, s101, v137
	s_sub_i32 s101, 0, s101
	s_waitcnt lgkmcnt(0)
	s_barrier

; __global__ __launch_bounds__(512, 2) void mega(Args aa) {
	.amdhsa_kernel _Z4mega4Args
		.amdhsa_group_segment_fixed_size 0
		.amdhsa_private_segment_fixed_size 0
		.amdhsa_kernarg_size 536
		.amdhsa_user_sgpr_count 2
		.amdhsa_user_sgpr_dispatch_ptr 0
		.amdhsa_user_sgpr_queue_ptr 0
		.amdhsa_user_sgpr_kernarg_segment_ptr 1
		.amdhsa_user_sgpr_dispatch_id 0
		.amdhsa_user_sgpr_kernarg_preload_length 0
		.amdhsa_user_sgpr_kernarg_preload_offset 0
		.amdhsa_user_sgpr_private_segment_size 0
		.amdhsa_uses_dynamic_stack 0
		.amdhsa_enable_private_segment 0
		.amdhsa_system_sgpr_workgroup_id_x 1
		.amdhsa_system_sgpr_workgroup_id_y 0
		.amdhsa_system_sgpr_workgroup_id_z 0
		.amdhsa_system_sgpr_workgroup_info 0
		.amdhsa_system_vgpr_workitem_id 2
		.amdhsa_next_free_vgpr 255
		.amdhsa_next_free_sgpr 102
		.amdhsa_accum_offset 256
		.amdhsa_reserve_vcc 1
		.amdhsa_float_round_mode_32 0
		.amdhsa_float_round_mode_16_64 0
		.amdhsa_float_denorm_mode_32 3
		.amdhsa_float_denorm_mode_16_64 3
		.amdhsa_dx10_clamp 1
		.amdhsa_ieee_mode 1
		.amdhsa_fp16_overflow 0
		.amdhsa_tg_split 0
		.amdhsa_exception_fp_ieee_invalid_op 0
		.amdhsa_exception_fp_denorm_src 0
		.amdhsa_exception_fp_ieee_div_zero 0
		.amdhsa_exception_fp_ieee_overflow 0
		.amdhsa_exception_fp_ieee_underflow 0
		.amdhsa_exception_fp_ieee_inexact 0
		.amdhsa_exception_int_div_zero 0
	.end_amdhsa_kernel

; __global__ __launch_bounds__(512, 2) void mega(Args aa) {
amdhsa.kernels:
  - .agpr_count:     0
    .args:
      - .offset:         0
        .size:           280
        .value_kind:     by_value
      - .offset:         280
        .size:           4
        .value_kind:     hidden_block_count_x
      - .offset:         284
        .size:           4
        .value_kind:     hidden_block_count_y
      - .offset:         288
        .size:           4
        .value_kind:     hidden_block_count_z
      - .offset:         292
        .size:           2
        .value_kind:     hidden_group_size_x
      - .offset:         294
        .size:           2
        .value_kind:     hidden_group_size_y
      - .offset:         296
        .size:           2
        .value_kind:     hidden_group_size_z
      - .offset:         298
        .size:           2
        .value_kind:     hidden_remainder_x
      - .offset:         300
        .size:           2
        .value_kind:     hidden_remainder_y
      - .offset:         302
        .size:           2
        .value_kind:     hidden_remainder_z
      - .offset:         320
        .size:           8
        .value_kind:     hidden_global_offset_x
      - .offset:         328
        .size:           8
        .value_kind:     hidden_global_offset_y
      - .offset:         336
        .size:           8
        .value_kind:     hidden_global_offset_z
      - .offset:         344
        .size:           2
        .value_kind:     hidden_grid_dims
      - .offset:         368
        .size:           8
        .value_kind:     hidden_multigrid_sync_arg
      - .offset:         400
        .size:           4
        .value_kind:     hidden_dynamic_lds_size
    .group_segment_fixed_size: 0
    .kernarg_segment_align: 8
    .kernarg_segment_size: 536
    .language:       OpenCL C
    .language_version:
      - 2
      - 0
    .max_flat_workgroup_size: 512
    .name:           _Z4mega4Args
    .private_segment_fixed_size: 0
    .sgpr_count:     108
    .sgpr_spill_count: 3
    .symbol:         _Z4mega4Args.kd
    .uniform_work_group_size: 1
    .uses_dynamic_stack: false
    .vgpr_count:     255
    .vgpr_spill_count: 0
    .wavefront_size: 64
